# per-tile accumulator zeroing: 128 v_mov_b32 -> 64 v_mov_b64 in all 14 GEMM instances
# baseline (speedup 1.0000x reference)
; template <class Epi, bool ALIGN_EPI = PG8_ALIGN>
; __device__ __forceinline__ void gemm_phase(LAS unsigned char* lds, const Gemm g, const StaticOrder S, const Epi E) {
;     ...
;         const bool has_next = S.next(ui + 1, nxt);
;         const char* nA = has_next ? (const char*)g.A + (size_t)nxt.pm * tstepA : cA; const char* nB = has_next ? (const char*)g.Bt + (size_t)nxt.pn * tstepB : cB;
;         for (int t = 0; t < nt; t += 2) {
;             const bool last = (t == nt - 2);
;             const char* a1 = cA + (size_t)(t + 1) * kstep;
;             const char* a2 = last ? nA : cA + (size_t)(t + 2) * kstep; const char* b2 = last ? nB : cB + (size_t)(t + 2) * kstep;
;             const char* a3 = a2 + kstep; const char* b3 = b2 + kstep;
;     ...
; #pragma unroll
;         for (int a = 0; a < 2; ++a)
; #pragma unroll
;             for (int b = 0; b < 2; ++b)
; #pragma unroll
;                 for (int m = 0; m < 4; ++m)
; #pragma unroll
;                     for (int n = 0; n < 2; ++n) acc[a][b][m][n] = (f32x4){0.f, 0.f, 0.f, 0.f};
;         cur = nxt; cA = nA; cB = nB; ++ui;
.LBB0_334:
	s_ashr_i32 s43, s42, 31
	s_lshl_b64 s[46:47], s[42:43], 20
	s_add_u32 s46, s40, s46
	s_addc_u32 s47, s41, s47
	s_and_b64 s[48:49], s[2:3], exec
	s_cselect_b32 s14, s47, s51
	s_cselect_b32 s35, s46, s50
	s_ashr_i32 s11, s10, 31
	s_lshl_b64 s[48:49], s[10:11], 20
	s_add_u32 s48, s86, s48
	s_addc_u32 s49, s87, s49
	s_and_b64 s[60:61], s[2:3], exec
	s_cselect_b32 s11, s49, s59
	s_cselect_b32 s43, s48, s58
	s_add_u32 s50, s50, 0x80080
	s_addc_u32 s51, s51, 0
	s_add_u32 s72, s58, 0x100
	v_mov_b64_e32 v[0:1], 0
	v_mov_b64_e32 v[2:3], 0
	v_mov_b64_e32 v[4:5], 0
	v_mov_b64_e32 v[6:7], 0
	v_mov_b64_e32 v[8:9], 0
	v_mov_b64_e32 v[10:11], 0
	v_mov_b64_e32 v[12:13], 0
	v_mov_b64_e32 v[14:15], 0
	v_mov_b64_e32 v[16:17], 0
	v_mov_b64_e32 v[18:19], 0
	v_mov_b64_e32 v[20:21], 0
	v_mov_b64_e32 v[22:23], 0
	v_mov_b64_e32 v[24:25], 0
	v_mov_b64_e32 v[26:27], 0
	v_mov_b64_e32 v[28:29], 0
	v_mov_b64_e32 v[30:31], 0
	v_mov_b64_e32 v[32:33], 0
	v_mov_b64_e32 v[34:35], 0
	v_mov_b64_e32 v[36:37], 0
	v_mov_b64_e32 v[38:39], 0
	v_mov_b64_e32 v[40:41], 0
	v_mov_b64_e32 v[42:43], 0
	v_mov_b64_e32 v[44:45], 0
	v_mov_b64_e32 v[46:47], 0
	v_mov_b64_e32 v[48:49], 0
	v_mov_b64_e32 v[50:51], 0
	v_mov_b64_e32 v[52:53], 0
	v_mov_b64_e32 v[54:55], 0
	v_mov_b64_e32 v[56:57], 0
	v_mov_b64_e32 v[58:59], 0
	v_mov_b64_e32 v[60:61], 0
	v_mov_b64_e32 v[62:63], 0
	v_mov_b64_e32 v[64:65], 0
	v_mov_b64_e32 v[66:67], 0
	v_mov_b64_e32 v[68:69], 0
	v_mov_b64_e32 v[70:71], 0
	v_mov_b64_e32 v[72:73], 0
	v_mov_b64_e32 v[74:75], 0
	v_mov_b64_e32 v[76:77], 0
	v_mov_b64_e32 v[78:79], 0
	v_mov_b64_e32 v[80:81], 0
	v_mov_b64_e32 v[82:83], 0
	v_mov_b64_e32 v[84:85], 0
	v_mov_b64_e32 v[86:87], 0
	v_mov_b64_e32 v[88:89], 0
	v_mov_b64_e32 v[90:91], 0
	v_mov_b64_e32 v[92:93], 0
	v_mov_b64_e32 v[94:95], 0
	v_mov_b64_e32 v[96:97], 0
	v_mov_b64_e32 v[98:99], 0
	v_mov_b64_e32 v[100:101], 0
	v_mov_b64_e32 v[102:103], 0
	v_mov_b64_e32 v[104:105], 0
	v_mov_b64_e32 v[106:107], 0
	v_mov_b64_e32 v[108:109], 0
	v_mov_b64_e32 v[110:111], 0
	v_mov_b64_e32 v[112:113], 0
	v_mov_b64_e32 v[114:115], 0
	v_mov_b64_e32 v[116:117], 0
	v_mov_b64_e32 v[118:119], 0
	v_mov_b64_e32 v[120:121], 0
	v_mov_b64_e32 v[122:123], 0
	v_mov_b64_e32 v[124:125], 0
	v_mov_b64_e32 v[126:127], 0
	s_addc_u32 s73, s59, 0
	s_mov_b32 s74, -2

; template <class Epi, bool ALIGN_EPI = PG8_ALIGN>
; __device__ __forceinline__ void gemm_phase(LAS unsigned char* lds, const Gemm g, const StaticOrder S, const Epi E) {
;     ...
;         const bool has_next = S.next(ui + 1, nxt);
;         const char* nA = has_next ? (const char*)g.A + (size_t)nxt.pm * tstepA : cA; const char* nB = has_next ? (const char*)g.Bt + (size_t)nxt.pn * tstepB : cB;
;         for (int t = 0; t < nt; t += 2) {
;             const bool last = (t == nt - 2);
;             const char* a1 = cA + (size_t)(t + 1) * kstep;
;             const char* a2 = last ? nA : cA + (size_t)(t + 2) * kstep; const char* b2 = last ? nB : cB + (size_t)(t + 2) * kstep;
;             const char* a3 = a2 + kstep; const char* b3 = b2 + kstep;
;     ...
; #pragma unroll
;         for (int a = 0; a < 2; ++a)
; #pragma unroll
;             for (int b = 0; b < 2; ++b)
; #pragma unroll
;                 for (int m = 0; m < 4; ++m)
; #pragma unroll
;                     for (int n = 0; n < 2; ++n) acc[a][b][m][n] = (f32x4){0.f, 0.f, 0.f, 0.f};
;         cur = nxt; cA = nA; cB = nB; ++ui;
.LBB0_419:
	s_add_u32 s12, s12, 0x160080
	s_addc_u32 s13, s13, 0
	s_add_u32 s17, s48, 0x100
	v_mov_b64_e32 v[0:1], 0
	v_mov_b64_e32 v[2:3], 0
	v_mov_b64_e32 v[4:5], 0
	v_mov_b64_e32 v[6:7], 0
	v_mov_b64_e32 v[8:9], 0
	v_mov_b64_e32 v[10:11], 0
	v_mov_b64_e32 v[12:13], 0
	v_mov_b64_e32 v[14:15], 0
	v_mov_b64_e32 v[16:17], 0
	v_mov_b64_e32 v[18:19], 0
	v_mov_b64_e32 v[20:21], 0
	v_mov_b64_e32 v[22:23], 0
	v_mov_b64_e32 v[24:25], 0
	v_mov_b64_e32 v[26:27], 0
	v_mov_b64_e32 v[28:29], 0
	v_mov_b64_e32 v[30:31], 0
	v_mov_b64_e32 v[32:33], 0
	v_mov_b64_e32 v[34:35], 0
	v_mov_b64_e32 v[36:37], 0
	v_mov_b64_e32 v[38:39], 0
	v_mov_b64_e32 v[40:41], 0
	v_mov_b64_e32 v[42:43], 0
	v_mov_b64_e32 v[44:45], 0
	v_mov_b64_e32 v[46:47], 0
	v_mov_b64_e32 v[48:49], 0
	v_mov_b64_e32 v[50:51], 0
	v_mov_b64_e32 v[52:53], 0
	v_mov_b64_e32 v[54:55], 0
	v_mov_b64_e32 v[56:57], 0
	v_mov_b64_e32 v[58:59], 0
	v_mov_b64_e32 v[60:61], 0
	v_mov_b64_e32 v[62:63], 0
	v_mov_b64_e32 v[64:65], 0
	v_mov_b64_e32 v[66:67], 0
	v_mov_b64_e32 v[68:69], 0
	v_mov_b64_e32 v[70:71], 0
	v_mov_b64_e32 v[72:73], 0
	v_mov_b64_e32 v[74:75], 0
	v_mov_b64_e32 v[76:77], 0
	v_mov_b64_e32 v[78:79], 0
	v_mov_b64_e32 v[80:81], 0
	v_mov_b64_e32 v[82:83], 0
	v_mov_b64_e32 v[84:85], 0
	v_mov_b64_e32 v[86:87], 0
	v_mov_b64_e32 v[88:89], 0
	v_mov_b64_e32 v[90:91], 0
	v_mov_b64_e32 v[92:93], 0
	v_mov_b64_e32 v[94:95], 0
	v_mov_b64_e32 v[96:97], 0
	v_mov_b64_e32 v[98:99], 0
	v_mov_b64_e32 v[100:101], 0
	v_mov_b64_e32 v[102:103], 0
	v_mov_b64_e32 v[104:105], 0
	v_mov_b64_e32 v[106:107], 0
	v_mov_b64_e32 v[108:109], 0
	v_mov_b64_e32 v[110:111], 0
	v_mov_b64_e32 v[112:113], 0
	v_mov_b64_e32 v[114:115], 0
	v_mov_b64_e32 v[116:117], 0
	v_mov_b64_e32 v[118:119], 0
	v_mov_b64_e32 v[120:121], 0
	v_mov_b64_e32 v[122:123], 0
	v_mov_b64_e32 v[124:125], 0
	v_mov_b64_e32 v[126:127], 0
	s_addc_u32 s33, s49, 0
	s_mov_b32 s34, -2

; template <class Epi, bool ALIGN_EPI = PG8_ALIGN>
; __device__ __forceinline__ void gemm_phase(LAS unsigned char* lds, const Gemm g, const StaticOrder S, const Epi E) {
;     ...
;         const bool has_next = S.next(ui + 1, nxt);
;         const char* nA = has_next ? (const char*)g.A + (size_t)nxt.pm * tstepA : cA; const char* nB = has_next ? (const char*)g.Bt + (size_t)nxt.pn * tstepB : cB;
;         for (int t = 0; t < nt; t += 2) {
;             const bool last = (t == nt - 2);
;             const char* a1 = cA + (size_t)(t + 1) * kstep;
;             const char* a2 = last ? nA : cA + (size_t)(t + 2) * kstep; const char* b2 = last ? nB : cB + (size_t)(t + 2) * kstep;
;             const char* a3 = a2 + kstep; const char* b3 = b2 + kstep;
;     ...
; #pragma unroll
;         for (int a = 0; a < 2; ++a)
; #pragma unroll
;             for (int b = 0; b < 2; ++b)
; #pragma unroll
;                 for (int m = 0; m < 4; ++m)
; #pragma unroll
;                     for (int n = 0; n < 2; ++n) acc[a][b][m][n] = (f32x4){0.f, 0.f, 0.f, 0.f};
;         cur = nxt; cA = nA; cB = nB; ++ui;
.LBB0_506:
	s_ashr_i32 s47, s46, 31
	s_waitcnt lgkmcnt(0)
	s_lshl_b64 s[16:17], s[46:47], 20
	s_add_u32 s48, s40, s16
	s_addc_u32 s49, s41, s17
	s_and_b64 s[16:17], s[2:3], exec
	s_cselect_b32 s14, s49, s53
	s_cselect_b32 s16, s48, s52
	s_ashr_i32 s11, s10, 31
	s_lshl_b64 s[34:35], s[10:11], 20
	s_add_u32 s50, s81, s34
	s_addc_u32 s51, s82, s35
	s_and_b64 s[34:35], s[2:3], exec
	s_cselect_b32 s11, s51, s59
	s_cselect_b32 s17, s50, s58
	s_add_u32 s52, s52, 0x80080
	s_addc_u32 s53, s53, 0
	s_add_u32 s33, s58, 0x100
	v_mov_b64_e32 v[0:1], 0
	v_mov_b64_e32 v[2:3], 0
	v_mov_b64_e32 v[4:5], 0
	v_mov_b64_e32 v[6:7], 0
	v_mov_b64_e32 v[8:9], 0
	v_mov_b64_e32 v[10:11], 0
	v_mov_b64_e32 v[12:13], 0
	v_mov_b64_e32 v[14:15], 0
	v_mov_b64_e32 v[16:17], 0
	v_mov_b64_e32 v[18:19], 0
	v_mov_b64_e32 v[20:21], 0
	v_mov_b64_e32 v[22:23], 0
	v_mov_b64_e32 v[24:25], 0
	v_mov_b64_e32 v[26:27], 0
	v_mov_b64_e32 v[28:29], 0
	v_mov_b64_e32 v[30:31], 0
	v_mov_b64_e32 v[32:33], 0
	v_mov_b64_e32 v[34:35], 0
	v_mov_b64_e32 v[36:37], 0
	v_mov_b64_e32 v[38:39], 0
	v_mov_b64_e32 v[40:41], 0
	v_mov_b64_e32 v[42:43], 0
	v_mov_b64_e32 v[44:45], 0
	v_mov_b64_e32 v[46:47], 0
	v_mov_b64_e32 v[48:49], 0
	v_mov_b64_e32 v[50:51], 0
	v_mov_b64_e32 v[52:53], 0
	v_mov_b64_e32 v[54:55], 0
	v_mov_b64_e32 v[56:57], 0
	v_mov_b64_e32 v[58:59], 0
	v_mov_b64_e32 v[60:61], 0
	v_mov_b64_e32 v[62:63], 0
	v_mov_b64_e32 v[64:65], 0
	v_mov_b64_e32 v[66:67], 0
	v_mov_b64_e32 v[68:69], 0
	v_mov_b64_e32 v[70:71], 0
	v_mov_b64_e32 v[72:73], 0
	v_mov_b64_e32 v[74:75], 0
	v_mov_b64_e32 v[76:77], 0
	v_mov_b64_e32 v[78:79], 0
	v_mov_b64_e32 v[80:81], 0
	v_mov_b64_e32 v[82:83], 0
	v_mov_b64_e32 v[84:85], 0
	v_mov_b64_e32 v[86:87], 0
	v_mov_b64_e32 v[88:89], 0
	v_mov_b64_e32 v[90:91], 0
	v_mov_b64_e32 v[92:93], 0
	v_mov_b64_e32 v[94:95], 0
	v_mov_b64_e32 v[96:97], 0
	v_mov_b64_e32 v[98:99], 0
	v_mov_b64_e32 v[100:101], 0
	v_mov_b64_e32 v[102:103], 0
	v_mov_b64_e32 v[104:105], 0
	v_mov_b64_e32 v[106:107], 0
	v_mov_b64_e32 v[108:109], 0
	v_mov_b64_e32 v[110:111], 0
	v_mov_b64_e32 v[112:113], 0
	v_mov_b64_e32 v[114:115], 0
	v_mov_b64_e32 v[116:117], 0
	v_mov_b64_e32 v[118:119], 0
	v_mov_b64_e32 v[120:121], 0
	v_mov_b64_e32 v[122:123], 0
	v_mov_b64_e32 v[124:125], 0
	v_mov_b64_e32 v[126:127], 0
	s_addc_u32 s34, s59, 0
	s_mov_b32 s35, -2

; template <class Epi, bool ALIGN_EPI = PG8_ALIGN>
; __device__ __forceinline__ void gemm_phase(LAS unsigned char* lds, const Gemm g, const StaticOrder S, const Epi E) {
;     ...
;         const bool has_next = S.next(ui + 1, nxt);
;         const char* nA = has_next ? (const char*)g.A + (size_t)nxt.pm * tstepA : cA; const char* nB = has_next ? (const char*)g.Bt + (size_t)nxt.pn * tstepB : cB;
;         for (int t = 0; t < nt; t += 2) {
;             const bool last = (t == nt - 2);
;             const char* a1 = cA + (size_t)(t + 1) * kstep;
;             const char* a2 = last ? nA : cA + (size_t)(t + 2) * kstep; const char* b2 = last ? nB : cB + (size_t)(t + 2) * kstep;
;             const char* a3 = a2 + kstep; const char* b3 = b2 + kstep;
;     ...
; #pragma unroll
;         for (int a = 0; a < 2; ++a)
; #pragma unroll
;             for (int b = 0; b < 2; ++b)
; #pragma unroll
;                 for (int m = 0; m < 4; ++m)
; #pragma unroll
;                     for (int n = 0; n < 2; ++n) acc[a][b][m][n] = (f32x4){0.f, 0.f, 0.f, 0.f};
;         cur = nxt; cA = nA; cB = nB; ++ui;
.LBB0_530:
	s_ashr_i32 s59, s58, 31
	s_lshl_b64 s[42:43], s[58:59], 20
	s_add_u32 s60, s16, s42
	s_addc_u32 s61, s17, s43
	s_and_b64 s[42:43], s[2:3], exec
	s_cselect_b32 s14, s61, s13
	s_cselect_b32 s59, s60, s12
	s_ashr_i32 s53, s52, 31
	s_lshl_b64 s[42:43], s[52:53], 20
	s_add_u32 s62, s40, s42
	s_addc_u32 s63, s41, s43
	s_and_b64 s[42:43], s[2:3], exec
	s_cselect_b32 s53, s63, s65
	s_cselect_b32 s93, s62, s64
	s_add_u32 s12, s12, 0x80080
	s_addc_u32 s13, s13, 0
	s_add_u32 s95, s64, 0x100
	v_mov_b64_e32 v[0:1], 0
	v_mov_b64_e32 v[2:3], 0
	v_mov_b64_e32 v[4:5], 0
	v_mov_b64_e32 v[6:7], 0
	v_mov_b64_e32 v[8:9], 0
	v_mov_b64_e32 v[10:11], 0
	v_mov_b64_e32 v[12:13], 0
	v_mov_b64_e32 v[14:15], 0
	v_mov_b64_e32 v[16:17], 0
	v_mov_b64_e32 v[18:19], 0
	v_mov_b64_e32 v[20:21], 0
	v_mov_b64_e32 v[22:23], 0
	v_mov_b64_e32 v[24:25], 0
	v_mov_b64_e32 v[26:27], 0
	v_mov_b64_e32 v[28:29], 0
	v_mov_b64_e32 v[30:31], 0
	v_mov_b64_e32 v[32:33], 0
	v_mov_b64_e32 v[34:35], 0
	v_mov_b64_e32 v[36:37], 0
	v_mov_b64_e32 v[38:39], 0
	v_mov_b64_e32 v[40:41], 0
	v_mov_b64_e32 v[42:43], 0
	v_mov_b64_e32 v[44:45], 0
	v_mov_b64_e32 v[46:47], 0
	v_mov_b64_e32 v[48:49], 0
	v_mov_b64_e32 v[50:51], 0
	v_mov_b64_e32 v[52:53], 0
	v_mov_b64_e32 v[54:55], 0
	v_mov_b64_e32 v[56:57], 0
	v_mov_b64_e32 v[58:59], 0
	v_mov_b64_e32 v[60:61], 0
	v_mov_b64_e32 v[62:63], 0
	v_mov_b64_e32 v[64:65], 0
	v_mov_b64_e32 v[66:67], 0
	v_mov_b64_e32 v[68:69], 0
	v_mov_b64_e32 v[70:71], 0
	v_mov_b64_e32 v[72:73], 0
	v_mov_b64_e32 v[74:75], 0
	v_mov_b64_e32 v[76:77], 0
	v_mov_b64_e32 v[78:79], 0
	v_mov_b64_e32 v[80:81], 0
	v_mov_b64_e32 v[82:83], 0
	v_mov_b64_e32 v[84:85], 0
	v_mov_b64_e32 v[86:87], 0
	v_mov_b64_e32 v[88:89], 0
	v_mov_b64_e32 v[90:91], 0
	v_mov_b64_e32 v[92:93], 0
	v_mov_b64_e32 v[94:95], 0
	v_mov_b64_e32 v[96:97], 0
	v_mov_b64_e32 v[98:99], 0
	v_mov_b64_e32 v[100:101], 0
	v_mov_b64_e32 v[102:103], 0
	v_mov_b64_e32 v[104:105], 0
	v_mov_b64_e32 v[106:107], 0
	v_mov_b64_e32 v[108:109], 0
	v_mov_b64_e32 v[110:111], 0
	v_mov_b64_e32 v[112:113], 0
	v_mov_b64_e32 v[114:115], 0
	v_mov_b64_e32 v[116:117], 0
	v_mov_b64_e32 v[118:119], 0
	v_mov_b64_e32 v[120:121], 0
	v_mov_b64_e32 v[122:123], 0
	v_mov_b64_e32 v[124:125], 0
	v_mov_b64_e32 v[126:127], 0
	s_addc_u32 s97, s65, 0
	s_mov_b32 vcc_lo, -2

; template <class Epi, bool ALIGN_EPI = PG8_ALIGN>
; __device__ __forceinline__ void gemm_phase(LAS unsigned char* lds, const Gemm g, const StaticOrder S, const Epi E) {
;     ...
;         const bool has_next = S.next(ui + 1, nxt);
;         const char* nA = has_next ? (const char*)g.A + (size_t)nxt.pm * tstepA : cA; const char* nB = has_next ? (const char*)g.Bt + (size_t)nxt.pn * tstepB : cB;
;         for (int t = 0; t < nt; t += 2) {
;             const bool last = (t == nt - 2);
;             const char* a1 = cA + (size_t)(t + 1) * kstep;
;             const char* a2 = last ? nA : cA + (size_t)(t + 2) * kstep; const char* b2 = last ? nB : cB + (size_t)(t + 2) * kstep;
;             const char* a3 = a2 + kstep; const char* b3 = b2 + kstep;
;     ...
; #pragma unroll
;         for (int a = 0; a < 2; ++a)
; #pragma unroll
;             for (int b = 0; b < 2; ++b)
; #pragma unroll
;                 for (int m = 0; m < 4; ++m)
; #pragma unroll
;                     for (int n = 0; n < 2; ++n) acc[a][b][m][n] = (f32x4){0.f, 0.f, 0.f, 0.f};
;         cur = nxt; cA = nA; cB = nB; ++ui;
.LBB0_868:
	s_ashr_i32 s29, s28, 31
	s_lshl_b64 s[0:1], s[28:29], 18
	s_add_u32 s36, s16, s0
	s_addc_u32 s37, s17, s1
	s_and_b64 s[0:1], s[2:3], exec
	s_cselect_b32 s29, s37, s51
	s_cselect_b32 s66, s36, s50
	s_ashr_i32 s27, s26, 31
	s_lshl_b64 s[0:1], s[26:27], 18
	s_add_u32 s44, s38, s0
	s_addc_u32 s45, s83, s1
	s_and_b64 s[0:1], s[2:3], exec
	s_cselect_b32 s27, s45, s53
	s_cselect_b32 s67, s44, s52
	s_add_u32 s50, s50, 0x20080
	s_addc_u32 s51, s51, 0
	s_add_u32 s68, s52, 0x100
	v_mov_b64_e32 v[0:1], 0
	v_mov_b64_e32 v[2:3], 0
	v_mov_b64_e32 v[4:5], 0
	v_mov_b64_e32 v[6:7], 0
	v_mov_b64_e32 v[8:9], 0
	v_mov_b64_e32 v[10:11], 0
	v_mov_b64_e32 v[12:13], 0
	v_mov_b64_e32 v[14:15], 0
	v_mov_b64_e32 v[16:17], 0
	v_mov_b64_e32 v[18:19], 0
	v_mov_b64_e32 v[20:21], 0
	v_mov_b64_e32 v[22:23], 0
	v_mov_b64_e32 v[24:25], 0
	v_mov_b64_e32 v[26:27], 0
	v_mov_b64_e32 v[28:29], 0
	v_mov_b64_e32 v[30:31], 0
	v_mov_b64_e32 v[32:33], 0
	v_mov_b64_e32 v[34:35], 0
	v_mov_b64_e32 v[36:37], 0
	v_mov_b64_e32 v[38:39], 0
	v_mov_b64_e32 v[40:41], 0
	v_mov_b64_e32 v[42:43], 0
	v_mov_b64_e32 v[44:45], 0
	v_mov_b64_e32 v[46:47], 0
	v_mov_b64_e32 v[48:49], 0
	v_mov_b64_e32 v[50:51], 0
	v_mov_b64_e32 v[52:53], 0
	v_mov_b64_e32 v[54:55], 0
	v_mov_b64_e32 v[56:57], 0
	v_mov_b64_e32 v[58:59], 0
	v_mov_b64_e32 v[60:61], 0
	v_mov_b64_e32 v[62:63], 0
	v_mov_b64_e32 v[64:65], 0
	v_mov_b64_e32 v[66:67], 0
	v_mov_b64_e32 v[68:69], 0
	v_mov_b64_e32 v[70:71], 0
	v_mov_b64_e32 v[72:73], 0
	v_mov_b64_e32 v[74:75], 0
	v_mov_b64_e32 v[76:77], 0
	v_mov_b64_e32 v[78:79], 0
	v_mov_b64_e32 v[80:81], 0
	v_mov_b64_e32 v[82:83], 0
	v_mov_b64_e32 v[84:85], 0
	v_mov_b64_e32 v[86:87], 0
	v_mov_b64_e32 v[88:89], 0
	v_mov_b64_e32 v[90:91], 0
	v_mov_b64_e32 v[92:93], 0
	v_mov_b64_e32 v[94:95], 0
	v_mov_b64_e32 v[96:97], 0
	v_mov_b64_e32 v[98:99], 0
	v_mov_b64_e32 v[100:101], 0
	v_mov_b64_e32 v[102:103], 0
	v_mov_b64_e32 v[104:105], 0
	v_mov_b64_e32 v[106:107], 0
	v_mov_b64_e32 v[108:109], 0
	v_mov_b64_e32 v[110:111], 0
	v_mov_b64_e32 v[112:113], 0
	v_mov_b64_e32 v[114:115], 0
	v_mov_b64_e32 v[116:117], 0
	v_mov_b64_e32 v[118:119], 0
	v_mov_b64_e32 v[120:121], 0
	v_mov_b64_e32 v[122:123], 0
	v_mov_b64_e32 v[124:125], 0
	v_mov_b64_e32 v[126:127], 0
	s_addc_u32 s69, s53, 0
	s_mov_b32 s71, -2

; template <class Epi, bool ALIGN_EPI = PG8_ALIGN>
; __device__ __forceinline__ void gemm_phase(LAS unsigned char* lds, const Gemm g, const StaticOrder S, const Epi E) {
;     ...
;         const bool has_next = S.next(ui + 1, nxt);
;         const char* nA = has_next ? (const char*)g.A + (size_t)nxt.pm * tstepA : cA; const char* nB = has_next ? (const char*)g.Bt + (size_t)nxt.pn * tstepB : cB;
;         for (int t = 0; t < nt; t += 2) {
;             const bool last = (t == nt - 2);
;             const char* a1 = cA + (size_t)(t + 1) * kstep;
;             const char* a2 = last ? nA : cA + (size_t)(t + 2) * kstep; const char* b2 = last ? nB : cB + (size_t)(t + 2) * kstep;
;             const char* a3 = a2 + kstep; const char* b3 = b2 + kstep;
;     ...
; #pragma unroll
;         for (int a = 0; a < 2; ++a)
; #pragma unroll
;             for (int b = 0; b < 2; ++b)
; #pragma unroll
;                 for (int m = 0; m < 4; ++m)
; #pragma unroll
;                     for (int n = 0; n < 2; ++n) acc[a][b][m][n] = (f32x4){0.f, 0.f, 0.f, 0.f};
;         cur = nxt; cA = nA; cB = nB; ++ui;
.LBB0_892:
	s_ashr_i32 s29, s28, 31
	s_lshl_b64 s[0:1], s[28:29], 17
	s_add_u32 s50, s71, s0
	s_addc_u32 s51, s72, s1
	s_and_b64 s[0:1], s[2:3], exec
	s_cselect_b32 s29, s51, s45
	s_cselect_b32 s83, s50, s44
	s_ashr_i32 s27, s26, 31
	s_lshl_b64 s[0:1], s[26:27], 17
	v_readlane_b32 s27, v238, 49
	s_add_u32 s52, s27, s0
	v_readlane_b32 s0, v238, 50
	s_addc_u32 s53, s0, s1
	s_and_b64 s[0:1], s[2:3], exec
	v_mov_b64_e32 v[0:1], 0
	v_mov_b64_e32 v[2:3], 0
	v_mov_b64_e32 v[4:5], 0
	v_mov_b64_e32 v[6:7], 0
	v_mov_b64_e32 v[8:9], 0
	v_mov_b64_e32 v[10:11], 0
	v_mov_b64_e32 v[12:13], 0
	v_mov_b64_e32 v[14:15], 0
	v_mov_b64_e32 v[16:17], 0
	v_mov_b64_e32 v[18:19], 0
	v_mov_b64_e32 v[20:21], 0
	v_mov_b64_e32 v[22:23], 0
	v_mov_b64_e32 v[24:25], 0
	v_mov_b64_e32 v[26:27], 0
	v_mov_b64_e32 v[28:29], 0
	v_mov_b64_e32 v[30:31], 0
	v_mov_b64_e32 v[32:33], 0
	v_mov_b64_e32 v[34:35], 0
	v_mov_b64_e32 v[36:37], 0
	v_mov_b64_e32 v[38:39], 0
	v_mov_b64_e32 v[40:41], 0
	v_mov_b64_e32 v[42:43], 0
	v_mov_b64_e32 v[44:45], 0
	v_mov_b64_e32 v[46:47], 0
	v_mov_b64_e32 v[48:49], 0
	v_mov_b64_e32 v[50:51], 0
	v_mov_b64_e32 v[52:53], 0
	v_mov_b64_e32 v[54:55], 0
	v_mov_b64_e32 v[56:57], 0
	v_mov_b64_e32 v[58:59], 0
	v_mov_b64_e32 v[60:61], 0
	v_mov_b64_e32 v[62:63], 0
	v_mov_b64_e32 v[64:65], 0
	v_mov_b64_e32 v[66:67], 0
	v_mov_b64_e32 v[68:69], 0
	v_mov_b64_e32 v[70:71], 0
	v_mov_b64_e32 v[72:73], 0
	v_mov_b64_e32 v[74:75], 0
	v_mov_b64_e32 v[76:77], 0
	v_mov_b64_e32 v[78:79], 0
	v_mov_b64_e32 v[80:81], 0
	v_mov_b64_e32 v[82:83], 0
	v_mov_b64_e32 v[84:85], 0
	v_mov_b64_e32 v[86:87], 0
	v_mov_b64_e32 v[88:89], 0
	v_mov_b64_e32 v[90:91], 0
	v_mov_b64_e32 v[92:93], 0
	v_mov_b64_e32 v[94:95], 0
	v_mov_b64_e32 v[96:97], 0
	v_mov_b64_e32 v[98:99], 0
	v_mov_b64_e32 v[100:101], 0
	v_mov_b64_e32 v[102:103], 0
	v_mov_b64_e32 v[104:105], 0
	v_mov_b64_e32 v[106:107], 0
	v_mov_b64_e32 v[108:109], 0
	v_mov_b64_e32 v[110:111], 0
	v_mov_b64_e32 v[112:113], 0
	v_mov_b64_e32 v[114:115], 0
	v_mov_b64_e32 v[116:117], 0
	v_mov_b64_e32 v[118:119], 0
	v_mov_b64_e32 v[120:121], 0
	v_mov_b64_e32 v[122:123], 0
	v_mov_b64_e32 v[124:125], 0
	v_mov_b64_e32 v[126:127], 0
	s_cselect_b32 s27, s53, s37
	s_cselect_b32 s90, s52, s36
	s_mov_b32 s60, 0
	s_mov_b64 s[54:55], -1
	s_mov_b64 s[58:59], 0

; template <class Epi, bool ALIGN_EPI = PG8_ALIGN>
; __device__ __forceinline__ void gemm_phase(LAS unsigned char* lds, const Gemm g, const StaticOrder S, const Epi E) {
;     ...
;         const bool has_next = S.next(ui + 1, nxt);
;         const char* nA = has_next ? (const char*)g.A + (size_t)nxt.pm * tstepA : cA; const char* nB = has_next ? (const char*)g.Bt + (size_t)nxt.pn * tstepB : cB;
;         for (int t = 0; t < nt; t += 2) {
;             const bool last = (t == nt - 2);
;             const char* a1 = cA + (size_t)(t + 1) * kstep;
;             const char* a2 = last ? nA : cA + (size_t)(t + 2) * kstep; const char* b2 = last ? nB : cB + (size_t)(t + 2) * kstep;
;             const char* a3 = a2 + kstep; const char* b3 = b2 + kstep;
;     ...
; #pragma unroll
;         for (int a = 0; a < 2; ++a)
; #pragma unroll
;             for (int b = 0; b < 2; ++b)
; #pragma unroll
;                 for (int m = 0; m < 4; ++m)
; #pragma unroll
;                     for (int n = 0; n < 2; ++n) acc[a][b][m][n] = (f32x4){0.f, 0.f, 0.f, 0.f};
;         cur = nxt; cA = nA; cB = nB; ++ui;
.LBB0_916:
	s_ashr_i32 s27, s26, 31
	s_lshl_b64 s[0:1], s[26:27], 17
	s_add_u32 s44, s14, s0
	s_addc_u32 s45, s16, s1
	s_and_b64 s[0:1], s[2:3], exec
	s_cselect_b32 s27, s45, s51
	s_cselect_b32 s81, s44, s50
	s_ashr_i32 s25, s24, 31
	s_lshl_b64 s[0:1], s[24:25], 17
	s_add_u32 s52, s71, s0
	s_addc_u32 s53, s72, s1
	s_and_b64 s[0:1], s[2:3], exec
	v_mov_b64_e32 v[0:1], 0
	v_mov_b64_e32 v[2:3], 0
	v_mov_b64_e32 v[4:5], 0
	v_mov_b64_e32 v[6:7], 0
	v_mov_b64_e32 v[8:9], 0
	v_mov_b64_e32 v[10:11], 0
	v_mov_b64_e32 v[12:13], 0
	v_mov_b64_e32 v[14:15], 0
	v_mov_b64_e32 v[16:17], 0
	v_mov_b64_e32 v[18:19], 0
	v_mov_b64_e32 v[20:21], 0
	v_mov_b64_e32 v[22:23], 0
	v_mov_b64_e32 v[24:25], 0
	v_mov_b64_e32 v[26:27], 0
	v_mov_b64_e32 v[28:29], 0
	v_mov_b64_e32 v[30:31], 0
	v_mov_b64_e32 v[32:33], 0
	v_mov_b64_e32 v[34:35], 0
	v_mov_b64_e32 v[36:37], 0
	v_mov_b64_e32 v[38:39], 0
	v_mov_b64_e32 v[40:41], 0
	v_mov_b64_e32 v[42:43], 0
	v_mov_b64_e32 v[44:45], 0
	v_mov_b64_e32 v[46:47], 0
	v_mov_b64_e32 v[48:49], 0
	v_mov_b64_e32 v[50:51], 0
	v_mov_b64_e32 v[52:53], 0
	v_mov_b64_e32 v[54:55], 0
	v_mov_b64_e32 v[56:57], 0
	v_mov_b64_e32 v[58:59], 0
	v_mov_b64_e32 v[60:61], 0
	v_mov_b64_e32 v[62:63], 0
	v_mov_b64_e32 v[64:65], 0
	v_mov_b64_e32 v[66:67], 0
	v_mov_b64_e32 v[68:69], 0
	v_mov_b64_e32 v[70:71], 0
	v_mov_b64_e32 v[72:73], 0
	v_mov_b64_e32 v[74:75], 0
	v_mov_b64_e32 v[76:77], 0
	v_mov_b64_e32 v[78:79], 0
	v_mov_b64_e32 v[80:81], 0
	v_mov_b64_e32 v[82:83], 0
	v_mov_b64_e32 v[84:85], 0
	v_mov_b64_e32 v[86:87], 0
	v_mov_b64_e32 v[88:89], 0
	v_mov_b64_e32 v[90:91], 0
	v_mov_b64_e32 v[92:93], 0
	v_mov_b64_e32 v[94:95], 0
	v_mov_b64_e32 v[96:97], 0
	v_mov_b64_e32 v[98:99], 0
	v_mov_b64_e32 v[100:101], 0
	v_mov_b64_e32 v[102:103], 0
	v_mov_b64_e32 v[104:105], 0
	v_mov_b64_e32 v[106:107], 0
	v_mov_b64_e32 v[108:109], 0
	v_mov_b64_e32 v[110:111], 0
	v_mov_b64_e32 v[112:113], 0
	v_mov_b64_e32 v[114:115], 0
	v_mov_b64_e32 v[116:117], 0
	v_mov_b64_e32 v[118:119], 0
	v_mov_b64_e32 v[120:121], 0
	v_mov_b64_e32 v[122:123], 0
	v_mov_b64_e32 v[124:125], 0
	v_mov_b64_e32 v[126:127], 0
	s_cselect_b32 s25, s53, s37
	s_cselect_b32 s82, s52, s36
	s_mov_b32 s60, 0
	s_mov_b64 s[54:55], -1
	s_mov_b64 s[58:59], 0

; template <class Epi, bool ALIGN_EPI = PG8_ALIGN>
; __device__ __forceinline__ void gemm_phase(LAS unsigned char* lds, const Gemm g, const StaticOrder S, const Epi E) {
;     ...
;         const bool has_next = S.next(ui + 1, nxt);
;         const char* nA = has_next ? (const char*)g.A + (size_t)nxt.pm * tstepA : cA; const char* nB = has_next ? (const char*)g.Bt + (size_t)nxt.pn * tstepB : cB;
;         for (int t = 0; t < nt; t += 2) {
;             const bool last = (t == nt - 2);
;             const char* a1 = cA + (size_t)(t + 1) * kstep;
;             const char* a2 = last ? nA : cA + (size_t)(t + 2) * kstep; const char* b2 = last ? nB : cB + (size_t)(t + 2) * kstep;
;             const char* a3 = a2 + kstep; const char* b3 = b2 + kstep;
;     ...
; #pragma unroll
;         for (int a = 0; a < 2; ++a)
; #pragma unroll
;             for (int b = 0; b < 2; ++b)
; #pragma unroll
;                 for (int m = 0; m < 4; ++m)
; #pragma unroll
;                     for (int n = 0; n < 2; ++n) acc[a][b][m][n] = (f32x4){0.f, 0.f, 0.f, 0.f};
;         cur = nxt; cA = nA; cB = nB; ++ui;
.LBB0_1204:
	s_ashr_i32 s37, s36, 31
	s_lshl_b64 s[16:17], s[36:37], 20
	s_add_u32 s38, s40, s16
	s_addc_u32 s39, s41, s17
	s_and_b64 s[16:17], s[4:5], exec
	s_cselect_b32 s13, s39, s47
	s_cselect_b32 s14, s38, s46
	s_ashr_i32 s29, s28, 31
	s_lshl_b64 s[16:17], s[28:29], 20
	v_readlane_b32 s29, v238, 40
	s_add_u32 s42, s29, s16
	v_readlane_b32 s16, v238, 41
	s_addc_u32 s43, s16, s17
	s_and_b64 s[16:17], s[4:5], exec
	s_cselect_b32 s16, s43, s49
	s_cselect_b32 s17, s42, s48
	s_add_u32 s46, s46, 0x80080
	s_addc_u32 s47, s47, 0
	s_add_u32 s29, s48, 0x100
	v_mov_b64_e32 v[0:1], 0
	v_mov_b64_e32 v[2:3], 0
	v_mov_b64_e32 v[4:5], 0
	v_mov_b64_e32 v[6:7], 0
	v_mov_b64_e32 v[8:9], 0
	v_mov_b64_e32 v[10:11], 0
	v_mov_b64_e32 v[12:13], 0
	v_mov_b64_e32 v[14:15], 0
	v_mov_b64_e32 v[16:17], 0
	v_mov_b64_e32 v[18:19], 0
	v_mov_b64_e32 v[20:21], 0
	v_mov_b64_e32 v[22:23], 0
	v_mov_b64_e32 v[24:25], 0
	v_mov_b64_e32 v[26:27], 0
	v_mov_b64_e32 v[28:29], 0
	v_mov_b64_e32 v[30:31], 0
	v_mov_b64_e32 v[32:33], 0
	v_mov_b64_e32 v[34:35], 0
	v_mov_b64_e32 v[36:37], 0
	v_mov_b64_e32 v[38:39], 0
	v_mov_b64_e32 v[40:41], 0
	v_mov_b64_e32 v[42:43], 0
	v_mov_b64_e32 v[44:45], 0
	v_mov_b64_e32 v[46:47], 0
	v_mov_b64_e32 v[48:49], 0
	v_mov_b64_e32 v[50:51], 0
	v_mov_b64_e32 v[52:53], 0
	v_mov_b64_e32 v[54:55], 0
	v_mov_b64_e32 v[56:57], 0
	v_mov_b64_e32 v[58:59], 0
	v_mov_b64_e32 v[60:61], 0
	v_mov_b64_e32 v[62:63], 0
	v_mov_b64_e32 v[64:65], 0
	v_mov_b64_e32 v[66:67], 0
	v_mov_b64_e32 v[68:69], 0
	v_mov_b64_e32 v[70:71], 0
	v_mov_b64_e32 v[72:73], 0
	v_mov_b64_e32 v[74:75], 0
	v_mov_b64_e32 v[76:77], 0
	v_mov_b64_e32 v[78:79], 0
	v_mov_b64_e32 v[80:81], 0
	v_mov_b64_e32 v[82:83], 0
	v_mov_b64_e32 v[84:85], 0
	v_mov_b64_e32 v[86:87], 0
	v_mov_b64_e32 v[88:89], 0
	v_mov_b64_e32 v[90:91], 0
	v_mov_b64_e32 v[92:93], 0
	v_mov_b64_e32 v[94:95], 0
	v_mov_b64_e32 v[96:97], 0
	v_mov_b64_e32 v[98:99], 0
	v_mov_b64_e32 v[100:101], 0
	v_mov_b64_e32 v[102:103], 0
	v_mov_b64_e32 v[104:105], 0
	v_mov_b64_e32 v[106:107], 0
	v_mov_b64_e32 v[108:109], 0
	v_mov_b64_e32 v[110:111], 0
	v_mov_b64_e32 v[112:113], 0
	v_mov_b64_e32 v[114:115], 0
	v_mov_b64_e32 v[116:117], 0
	v_mov_b64_e32 v[118:119], 0
	v_mov_b64_e32 v[120:121], 0
	v_mov_b64_e32 v[122:123], 0
	v_mov_b64_e32 v[124:125], 0
	v_mov_b64_e32 v[126:127], 0
	s_addc_u32 s33, s49, 0
	s_mov_b32 s34, -2

; template <class Epi, bool ALIGN_EPI = PG8_ALIGN>
; __device__ __forceinline__ void gemm_phase(LAS unsigned char* lds, const Gemm g, const StaticOrder S, const Epi E) {
;     ...
;         const bool has_next = S.next(ui + 1, nxt);
;         const char* nA = has_next ? (const char*)g.A + (size_t)nxt.pm * tstepA : cA; const char* nB = has_next ? (const char*)g.Bt + (size_t)nxt.pn * tstepB : cB;
;         for (int t = 0; t < nt; t += 2) {
;             const bool last = (t == nt - 2);
;             const char* a1 = cA + (size_t)(t + 1) * kstep;
;             const char* a2 = last ? nA : cA + (size_t)(t + 2) * kstep; const char* b2 = last ? nB : cB + (size_t)(t + 2) * kstep;
;             const char* a3 = a2 + kstep; const char* b3 = b2 + kstep;
;     ...
; #pragma unroll
;         for (int a = 0; a < 2; ++a)
; #pragma unroll
;             for (int b = 0; b < 2; ++b)
; #pragma unroll
;                 for (int m = 0; m < 4; ++m)
; #pragma unroll
;                     for (int n = 0; n < 2; ++n) acc[a][b][m][n] = (f32x4){0.f, 0.f, 0.f, 0.f};
;         cur = nxt; cA = nA; cB = nB; ++ui;
.LBB0_1299:
	s_ashr_i32 s47, s46, 31
	s_lshl_b64 s[48:49], s[46:47], 20
	s_add_u32 s48, s6, s48
	s_addc_u32 s49, s7, s49
	s_and_b64 s[50:51], s[2:3], exec
	s_cselect_b32 s47, s49, s53
	s_cselect_b32 s69, s48, s52
	s_ashr_i32 s45, s44, 31
	s_lshl_b64 s[50:51], s[44:45], 20
	v_readlane_b32 s45, v238, 44
	s_add_u32 s50, s45, s50
	v_readlane_b32 s45, v238, 45
	s_addc_u32 s51, s45, s51
	s_and_b64 s[56:57], s[2:3], exec
	s_cselect_b32 s45, s51, s55
	s_cselect_b32 s70, s50, s54
	s_add_u32 s52, s52, 0x80080
	s_addc_u32 s53, s53, 0
	s_add_u32 s71, s54, 0x100
	v_mov_b64_e32 v[0:1], 0
	v_mov_b64_e32 v[2:3], 0
	v_mov_b64_e32 v[4:5], 0
	v_mov_b64_e32 v[6:7], 0
	v_mov_b64_e32 v[8:9], 0
	v_mov_b64_e32 v[10:11], 0
	v_mov_b64_e32 v[12:13], 0
	v_mov_b64_e32 v[14:15], 0
	v_mov_b64_e32 v[16:17], 0
	v_mov_b64_e32 v[18:19], 0
	v_mov_b64_e32 v[20:21], 0
	v_mov_b64_e32 v[22:23], 0
	v_mov_b64_e32 v[24:25], 0
	v_mov_b64_e32 v[26:27], 0
	v_mov_b64_e32 v[28:29], 0
	v_mov_b64_e32 v[30:31], 0
	v_mov_b64_e32 v[32:33], 0
	v_mov_b64_e32 v[34:35], 0
	v_mov_b64_e32 v[36:37], 0
	v_mov_b64_e32 v[38:39], 0
	v_mov_b64_e32 v[40:41], 0
	v_mov_b64_e32 v[42:43], 0
	v_mov_b64_e32 v[44:45], 0
	v_mov_b64_e32 v[46:47], 0
	v_mov_b64_e32 v[48:49], 0
	v_mov_b64_e32 v[50:51], 0
	v_mov_b64_e32 v[52:53], 0
	v_mov_b64_e32 v[54:55], 0
	v_mov_b64_e32 v[56:57], 0
	v_mov_b64_e32 v[58:59], 0
	v_mov_b64_e32 v[60:61], 0
	v_mov_b64_e32 v[62:63], 0
	v_mov_b64_e32 v[64:65], 0
	v_mov_b64_e32 v[66:67], 0
	v_mov_b64_e32 v[68:69], 0
	v_mov_b64_e32 v[70:71], 0
	v_mov_b64_e32 v[72:73], 0
	v_mov_b64_e32 v[74:75], 0
	v_mov_b64_e32 v[76:77], 0
	v_mov_b64_e32 v[78:79], 0
	v_mov_b64_e32 v[80:81], 0
	v_mov_b64_e32 v[82:83], 0
	v_mov_b64_e32 v[84:85], 0
	v_mov_b64_e32 v[86:87], 0
	v_mov_b64_e32 v[88:89], 0
	v_mov_b64_e32 v[90:91], 0
	v_mov_b64_e32 v[92:93], 0
	v_mov_b64_e32 v[94:95], 0
	v_mov_b64_e32 v[96:97], 0
	v_mov_b64_e32 v[98:99], 0
	v_mov_b64_e32 v[100:101], 0
	v_mov_b64_e32 v[102:103], 0
	v_mov_b64_e32 v[104:105], 0
	v_mov_b64_e32 v[106:107], 0
	v_mov_b64_e32 v[108:109], 0
	v_mov_b64_e32 v[110:111], 0
	v_mov_b64_e32 v[112:113], 0
	v_mov_b64_e32 v[114:115], 0
	v_mov_b64_e32 v[116:117], 0
	v_mov_b64_e32 v[118:119], 0
	v_mov_b64_e32 v[120:121], 0
	v_mov_b64_e32 v[122:123], 0
	v_mov_b64_e32 v[124:125], 0
	v_mov_b64_e32 v[126:127], 0
	s_addc_u32 s72, s55, 0
	s_mov_b32 s73, -2

; template <class Epi, bool ALIGN_EPI = PG8_ALIGN>
; __device__ __forceinline__ void gemm_phase(LAS unsigned char* lds, const Gemm g, const StaticOrder S, const Epi E) {
;     ...
;         const bool has_next = S.next(ui + 1, nxt);
;         const char* nA = has_next ? (const char*)g.A + (size_t)nxt.pm * tstepA : cA; const char* nB = has_next ? (const char*)g.Bt + (size_t)nxt.pn * tstepB : cB;
;         for (int t = 0; t < nt; t += 2) {
;             const bool last = (t == nt - 2);
;             const char* a1 = cA + (size_t)(t + 1) * kstep;
;             const char* a2 = last ? nA : cA + (size_t)(t + 2) * kstep; const char* b2 = last ? nB : cB + (size_t)(t + 2) * kstep;
;             const char* a3 = a2 + kstep; const char* b3 = b2 + kstep;
;     ...
; #pragma unroll
;         for (int a = 0; a < 2; ++a)
; #pragma unroll
;             for (int b = 0; b < 2; ++b)
; #pragma unroll
;                 for (int m = 0; m < 4; ++m)
; #pragma unroll
;                     for (int n = 0; n < 2; ++n) acc[a][b][m][n] = (f32x4){0.f, 0.f, 0.f, 0.f};
;         cur = nxt; cA = nA; cB = nB; ++ui;
.LBB0_1323:
	s_ashr_i32 s45, s44, 31
	s_lshl_b64 s[46:47], s[44:45], 20
	s_add_u32 s46, s56, s46
	s_addc_u32 s47, s57, s47
	s_and_b64 s[48:49], s[36:37], exec
	s_cselect_b32 s45, s47, s51
	s_cselect_b32 s71, s46, s50
	s_ashr_i32 s43, s42, 31
	s_lshl_b64 s[48:49], s[42:43], 20
	v_readlane_b32 s43, v238, 42
	s_add_u32 s48, s43, s48
	v_readlane_b32 s43, v238, 43
	s_addc_u32 s49, s43, s49
	s_and_b64 s[54:55], s[36:37], exec
	s_cselect_b32 s43, s49, s53
	s_cselect_b32 s72, s48, s52
	s_add_u32 s50, s50, 0x80080
	s_addc_u32 s51, s51, 0
	s_add_u32 s73, s52, 0x100
	v_mov_b64_e32 v[0:1], 0
	v_mov_b64_e32 v[2:3], 0
	v_mov_b64_e32 v[4:5], 0
	v_mov_b64_e32 v[6:7], 0
	v_mov_b64_e32 v[8:9], 0
	v_mov_b64_e32 v[10:11], 0
	v_mov_b64_e32 v[12:13], 0
	v_mov_b64_e32 v[14:15], 0
	v_mov_b64_e32 v[16:17], 0
	v_mov_b64_e32 v[18:19], 0
	v_mov_b64_e32 v[20:21], 0
	v_mov_b64_e32 v[22:23], 0
	v_mov_b64_e32 v[24:25], 0
	v_mov_b64_e32 v[26:27], 0
	v_mov_b64_e32 v[28:29], 0
	v_mov_b64_e32 v[30:31], 0
	v_mov_b64_e32 v[32:33], 0
	v_mov_b64_e32 v[34:35], 0
	v_mov_b64_e32 v[36:37], 0
	v_mov_b64_e32 v[38:39], 0
	v_mov_b64_e32 v[40:41], 0
	v_mov_b64_e32 v[42:43], 0
	v_mov_b64_e32 v[44:45], 0
	v_mov_b64_e32 v[46:47], 0
	v_mov_b64_e32 v[48:49], 0
	v_mov_b64_e32 v[50:51], 0
	v_mov_b64_e32 v[52:53], 0
	v_mov_b64_e32 v[54:55], 0
	v_mov_b64_e32 v[56:57], 0
	v_mov_b64_e32 v[58:59], 0
	v_mov_b64_e32 v[60:61], 0
	v_mov_b64_e32 v[62:63], 0
	v_mov_b64_e32 v[64:65], 0
	v_mov_b64_e32 v[66:67], 0
	v_mov_b64_e32 v[68:69], 0
	v_mov_b64_e32 v[70:71], 0
	v_mov_b64_e32 v[72:73], 0
	v_mov_b64_e32 v[74:75], 0
	v_mov_b64_e32 v[76:77], 0
	v_mov_b64_e32 v[78:79], 0
	v_mov_b64_e32 v[80:81], 0
	v_mov_b64_e32 v[82:83], 0
	v_mov_b64_e32 v[84:85], 0
	v_mov_b64_e32 v[86:87], 0
	v_mov_b64_e32 v[88:89], 0
	v_mov_b64_e32 v[90:91], 0
	v_mov_b64_e32 v[92:93], 0
	v_mov_b64_e32 v[94:95], 0
	v_mov_b64_e32 v[96:97], 0
	v_mov_b64_e32 v[98:99], 0
	v_mov_b64_e32 v[100:101], 0
	v_mov_b64_e32 v[102:103], 0
	v_mov_b64_e32 v[104:105], 0
	v_mov_b64_e32 v[106:107], 0
	v_mov_b64_e32 v[108:109], 0
	v_mov_b64_e32 v[110:111], 0
	v_mov_b64_e32 v[112:113], 0
	v_mov_b64_e32 v[114:115], 0
	v_mov_b64_e32 v[116:117], 0
	v_mov_b64_e32 v[118:119], 0
	v_mov_b64_e32 v[120:121], 0
	v_mov_b64_e32 v[122:123], 0
	v_mov_b64_e32 v[124:125], 0
	v_mov_b64_e32 v[126:127], 0
	s_addc_u32 s74, s53, 0
	s_mov_b32 s75, -2

; template <class Epi, bool ALIGN_EPI = PG8_ALIGN>
; __device__ __forceinline__ void gemm_phase(LAS unsigned char* lds, const Gemm g, const StaticOrder S, const Epi E) {
;     ...
;         const bool has_next = S.next(ui + 1, nxt);
;         const char* nA = has_next ? (const char*)g.A + (size_t)nxt.pm * tstepA : cA; const char* nB = has_next ? (const char*)g.Bt + (size_t)nxt.pn * tstepB : cB;
;         for (int t = 0; t < nt; t += 2) {
;             const bool last = (t == nt - 2);
;             const char* a1 = cA + (size_t)(t + 1) * kstep;
;             const char* a2 = last ? nA : cA + (size_t)(t + 2) * kstep; const char* b2 = last ? nB : cB + (size_t)(t + 2) * kstep;
;             const char* a3 = a2 + kstep; const char* b3 = b2 + kstep;
;     ...
; #pragma unroll
;         for (int a = 0; a < 2; ++a)
; #pragma unroll
;             for (int b = 0; b < 2; ++b)
; #pragma unroll
;                 for (int m = 0; m < 4; ++m)
; #pragma unroll
;                     for (int n = 0; n < 2; ++n) acc[a][b][m][n] = (f32x4){0.f, 0.f, 0.f, 0.f};
;         cur = nxt; cA = nA; cB = nB; ++ui;
.LBB0_1347:
	s_ashr_i32 s45, s44, 31
	s_lshl_b64 s[46:47], s[44:45], 20
	s_add_u32 s46, s17, s46
	s_addc_u32 s47, s33, s47
	s_and_b64 s[48:49], s[36:37], exec
	s_cselect_b32 s45, s47, s51
	s_cselect_b32 s71, s46, s50
	s_ashr_i32 s43, s42, 31
	s_lshl_b64 s[48:49], s[42:43], 20
	s_add_u32 s48, s56, s48
	s_addc_u32 s49, s57, s49
	s_and_b64 s[54:55], s[36:37], exec
	s_cselect_b32 s43, s49, s53
	s_cselect_b32 s72, s48, s52
	s_add_u32 s50, s50, 0x80080
	s_addc_u32 s51, s51, 0
	s_add_u32 s73, s52, 0x100
	v_mov_b64_e32 v[0:1], 0
	v_mov_b64_e32 v[2:3], 0
	v_mov_b64_e32 v[4:5], 0
	v_mov_b64_e32 v[6:7], 0
	v_mov_b64_e32 v[8:9], 0
	v_mov_b64_e32 v[10:11], 0
	v_mov_b64_e32 v[12:13], 0
	v_mov_b64_e32 v[14:15], 0
	v_mov_b64_e32 v[16:17], 0
	v_mov_b64_e32 v[18:19], 0
	v_mov_b64_e32 v[20:21], 0
	v_mov_b64_e32 v[22:23], 0
	v_mov_b64_e32 v[24:25], 0
	v_mov_b64_e32 v[26:27], 0
	v_mov_b64_e32 v[28:29], 0
	v_mov_b64_e32 v[30:31], 0
	v_mov_b64_e32 v[32:33], 0
	v_mov_b64_e32 v[34:35], 0
	v_mov_b64_e32 v[36:37], 0
	v_mov_b64_e32 v[38:39], 0
	v_mov_b64_e32 v[40:41], 0
	v_mov_b64_e32 v[42:43], 0
	v_mov_b64_e32 v[44:45], 0
	v_mov_b64_e32 v[46:47], 0
	v_mov_b64_e32 v[48:49], 0
	v_mov_b64_e32 v[50:51], 0
	v_mov_b64_e32 v[52:53], 0
	v_mov_b64_e32 v[54:55], 0
	v_mov_b64_e32 v[56:57], 0
	v_mov_b64_e32 v[58:59], 0
	v_mov_b64_e32 v[60:61], 0
	v_mov_b64_e32 v[62:63], 0
	v_mov_b64_e32 v[64:65], 0
	v_mov_b64_e32 v[66:67], 0
	v_mov_b64_e32 v[68:69], 0
	v_mov_b64_e32 v[70:71], 0
	v_mov_b64_e32 v[72:73], 0
	v_mov_b64_e32 v[74:75], 0
	v_mov_b64_e32 v[76:77], 0
	v_mov_b64_e32 v[78:79], 0
	v_mov_b64_e32 v[80:81], 0
	v_mov_b64_e32 v[82:83], 0
	v_mov_b64_e32 v[84:85], 0
	v_mov_b64_e32 v[86:87], 0
	v_mov_b64_e32 v[88:89], 0
	v_mov_b64_e32 v[90:91], 0
	v_mov_b64_e32 v[92:93], 0
	v_mov_b64_e32 v[94:95], 0
	v_mov_b64_e32 v[96:97], 0
	v_mov_b64_e32 v[98:99], 0
	v_mov_b64_e32 v[100:101], 0
	v_mov_b64_e32 v[102:103], 0
	v_mov_b64_e32 v[104:105], 0
	v_mov_b64_e32 v[106:107], 0
	v_mov_b64_e32 v[108:109], 0
	v_mov_b64_e32 v[110:111], 0
	v_mov_b64_e32 v[112:113], 0
	v_mov_b64_e32 v[114:115], 0
	v_mov_b64_e32 v[116:117], 0
	v_mov_b64_e32 v[118:119], 0
	v_mov_b64_e32 v[120:121], 0
	v_mov_b64_e32 v[122:123], 0
	v_mov_b64_e32 v[124:125], 0
	v_mov_b64_e32 v[126:127], 0
	s_addc_u32 s74, s53, 0
	s_mov_b32 s75, -2

; template <class Epi, bool ALIGN_EPI = PG8_ALIGN>
; __device__ __forceinline__ void gemm_phase(LAS unsigned char* lds, const Gemm g, const StaticOrder S, const Epi E) {
;     ...
;         const bool has_next = S.next(ui + 1, nxt);
;         const char* nA = has_next ? (const char*)g.A + (size_t)nxt.pm * tstepA : cA; const char* nB = has_next ? (const char*)g.Bt + (size_t)nxt.pn * tstepB : cB;
;         for (int t = 0; t < nt; t += 2) {
;             const bool last = (t == nt - 2);
;             const char* a1 = cA + (size_t)(t + 1) * kstep;
;             const char* a2 = last ? nA : cA + (size_t)(t + 2) * kstep; const char* b2 = last ? nB : cB + (size_t)(t + 2) * kstep;
;             const char* a3 = a2 + kstep; const char* b3 = b2 + kstep;
;     ...
; #pragma unroll
;         for (int a = 0; a < 2; ++a)
; #pragma unroll
;             for (int b = 0; b < 2; ++b)
; #pragma unroll
;                 for (int m = 0; m < 4; ++m)
; #pragma unroll
;                     for (int n = 0; n < 2; ++n) acc[a][b][m][n] = (f32x4){0.f, 0.f, 0.f, 0.f};
;         cur = nxt; cA = nA; cB = nB; ++ui;
.LBB0_1601:
	s_ashr_i32 s23, s22, 31
	s_lshl_b64 s[16:17], s[22:23], 18
	s_add_u32 s24, s64, s16
	s_addc_u32 s25, s65, s17
	s_and_b64 s[16:17], s[4:5], exec
	s_cselect_b32 s13, s25, s37
	s_cselect_b32 s14, s24, s36
	s_ashr_i32 s21, s20, 31
	s_lshl_b64 s[16:17], s[20:21], 18
	s_add_u32 s26, s58, s16
	s_addc_u32 s27, s59, s17
	s_and_b64 s[16:17], s[4:5], exec
	s_cselect_b32 s16, s27, s39
	s_cselect_b32 s17, s26, s38
	s_add_u32 s36, s36, 0x20080
	s_addc_u32 s37, s37, 0
	s_add_u32 s21, s38, 0x100
	v_mov_b64_e32 v[0:1], 0
	v_mov_b64_e32 v[2:3], 0
	v_mov_b64_e32 v[4:5], 0
	v_mov_b64_e32 v[6:7], 0
	v_mov_b64_e32 v[8:9], 0
	v_mov_b64_e32 v[10:11], 0
	v_mov_b64_e32 v[12:13], 0
	v_mov_b64_e32 v[14:15], 0
	v_mov_b64_e32 v[16:17], 0
	v_mov_b64_e32 v[18:19], 0
	v_mov_b64_e32 v[20:21], 0
	v_mov_b64_e32 v[22:23], 0
	v_mov_b64_e32 v[24:25], 0
	v_mov_b64_e32 v[26:27], 0
	v_mov_b64_e32 v[28:29], 0
	v_mov_b64_e32 v[30:31], 0
	v_mov_b64_e32 v[32:33], 0
	v_mov_b64_e32 v[34:35], 0
	v_mov_b64_e32 v[36:37], 0
	v_mov_b64_e32 v[38:39], 0
	v_mov_b64_e32 v[40:41], 0
	v_mov_b64_e32 v[42:43], 0
	v_mov_b64_e32 v[44:45], 0
	v_mov_b64_e32 v[46:47], 0
	v_mov_b64_e32 v[48:49], 0
	v_mov_b64_e32 v[50:51], 0
	v_mov_b64_e32 v[52:53], 0
	v_mov_b64_e32 v[54:55], 0
	v_mov_b64_e32 v[56:57], 0
	v_mov_b64_e32 v[58:59], 0
	v_mov_b64_e32 v[60:61], 0
	v_mov_b64_e32 v[62:63], 0
	v_mov_b64_e32 v[64:65], 0
	v_mov_b64_e32 v[66:67], 0
	v_mov_b64_e32 v[68:69], 0
	v_mov_b64_e32 v[70:71], 0
	v_mov_b64_e32 v[72:73], 0
	v_mov_b64_e32 v[74:75], 0
	v_mov_b64_e32 v[76:77], 0
	v_mov_b64_e32 v[78:79], 0
	v_mov_b64_e32 v[80:81], 0
	v_mov_b64_e32 v[82:83], 0
	v_mov_b64_e32 v[84:85], 0
	v_mov_b64_e32 v[86:87], 0
	v_mov_b64_e32 v[88:89], 0
	v_mov_b64_e32 v[90:91], 0
	v_mov_b64_e32 v[92:93], 0
	v_mov_b64_e32 v[94:95], 0
	v_mov_b64_e32 v[96:97], 0
	v_mov_b64_e32 v[98:99], 0
	v_mov_b64_e32 v[100:101], 0
	v_mov_b64_e32 v[102:103], 0
	v_mov_b64_e32 v[104:105], 0
	v_mov_b64_e32 v[106:107], 0
	v_mov_b64_e32 v[108:109], 0
	v_mov_b64_e32 v[110:111], 0
	v_mov_b64_e32 v[112:113], 0
	v_mov_b64_e32 v[114:115], 0
	v_mov_b64_e32 v[116:117], 0
	v_mov_b64_e32 v[118:119], 0
	v_mov_b64_e32 v[120:121], 0
	v_mov_b64_e32 v[122:123], 0
	v_mov_b64_e32 v[124:125], 0
	v_mov_b64_e32 v[126:127], 0
	s_addc_u32 s23, s39, 0
	s_mov_b32 s33, -2

; template <class Epi, bool ALIGN_EPI = PG8_ALIGN>
; __device__ __forceinline__ void gemm_phase(LAS unsigned char* lds, const Gemm g, const StaticOrder S, const Epi E) {
;     ...
;         const bool has_next = S.next(ui + 1, nxt);
;         const char* nA = has_next ? (const char*)g.A + (size_t)nxt.pm * tstepA : cA; const char* nB = has_next ? (const char*)g.Bt + (size_t)nxt.pn * tstepB : cB;
;         for (int t = 0; t < nt; t += 2) {
;             const bool last = (t == nt - 2);
;             const char* a1 = cA + (size_t)(t + 1) * kstep;
;             const char* a2 = last ? nA : cA + (size_t)(t + 2) * kstep; const char* b2 = last ? nB : cB + (size_t)(t + 2) * kstep;
;             const char* a3 = a2 + kstep; const char* b3 = b2 + kstep;
;     ...
; #pragma unroll
;         for (int a = 0; a < 2; ++a)
; #pragma unroll
;             for (int b = 0; b < 2; ++b)
; #pragma unroll
;                 for (int m = 0; m < 4; ++m)
; #pragma unroll
;                     for (int n = 0; n < 2; ++n) acc[a][b][m][n] = (f32x4){0.f, 0.f, 0.f, 0.f};
;         cur = nxt; cA = nA; cB = nB; ++ui;
.LBB0_1688:
	s_ashr_i32 s23, s22, 31
	s_lshl_b64 s[24:25], s[22:23], 20
	s_add_u32 s24, s40, s24
	s_addc_u32 s25, s41, s25
	s_and_b64 s[26:27], s[2:3], exec
	s_cselect_b32 s14, s25, s13
	s_cselect_b32 s23, s24, s12
	s_ashr_i32 s21, s20, 31
	s_lshl_b64 s[26:27], s[20:21], 20
	s_add_u32 s26, s86, s26
	s_addc_u32 s27, s87, s27
	s_and_b64 s[36:37], s[2:3], exec
	s_cselect_b32 s21, s27, s29
	s_cselect_b32 s50, s26, s28
	s_add_u32 s12, s12, 0x80080
	s_addc_u32 s13, s13, 0
	s_add_u32 s51, s28, 0x100
	v_mov_b64_e32 v[0:1], 0
	v_mov_b64_e32 v[2:3], 0
	v_mov_b64_e32 v[4:5], 0
	v_mov_b64_e32 v[6:7], 0
	v_mov_b64_e32 v[8:9], 0
	v_mov_b64_e32 v[10:11], 0
	v_mov_b64_e32 v[12:13], 0
	v_mov_b64_e32 v[14:15], 0
	v_mov_b64_e32 v[16:17], 0
	v_mov_b64_e32 v[18:19], 0
	v_mov_b64_e32 v[20:21], 0
	v_mov_b64_e32 v[22:23], 0
	v_mov_b64_e32 v[24:25], 0
	v_mov_b64_e32 v[26:27], 0
	v_mov_b64_e32 v[28:29], 0
	v_mov_b64_e32 v[30:31], 0
	v_mov_b64_e32 v[32:33], 0
	v_mov_b64_e32 v[34:35], 0
	v_mov_b64_e32 v[36:37], 0
	v_mov_b64_e32 v[38:39], 0
	v_mov_b64_e32 v[40:41], 0
	v_mov_b64_e32 v[42:43], 0
	v_mov_b64_e32 v[44:45], 0
	v_mov_b64_e32 v[46:47], 0
	v_mov_b64_e32 v[48:49], 0
	v_mov_b64_e32 v[50:51], 0
	v_mov_b64_e32 v[52:53], 0
	v_mov_b64_e32 v[54:55], 0
	v_mov_b64_e32 v[56:57], 0
	v_mov_b64_e32 v[58:59], 0
	v_mov_b64_e32 v[60:61], 0
	v_mov_b64_e32 v[62:63], 0
	v_mov_b64_e32 v[64:65], 0
	v_mov_b64_e32 v[66:67], 0
	v_mov_b64_e32 v[68:69], 0
	v_mov_b64_e32 v[70:71], 0
	v_mov_b64_e32 v[72:73], 0
	v_mov_b64_e32 v[74:75], 0
	v_mov_b64_e32 v[76:77], 0
	v_mov_b64_e32 v[78:79], 0
	v_mov_b64_e32 v[80:81], 0
	v_mov_b64_e32 v[82:83], 0
	v_mov_b64_e32 v[84:85], 0
	v_mov_b64_e32 v[86:87], 0
	v_mov_b64_e32 v[88:89], 0
	v_mov_b64_e32 v[90:91], 0
	v_mov_b64_e32 v[92:93], 0
	v_mov_b64_e32 v[94:95], 0
	v_mov_b64_e32 v[96:97], 0
	v_mov_b64_e32 v[98:99], 0
	v_mov_b64_e32 v[100:101], 0
	v_mov_b64_e32 v[102:103], 0
	v_mov_b64_e32 v[104:105], 0
	v_mov_b64_e32 v[106:107], 0
	v_mov_b64_e32 v[108:109], 0
	v_mov_b64_e32 v[110:111], 0
	v_mov_b64_e32 v[112:113], 0
	v_mov_b64_e32 v[114:115], 0
	v_mov_b64_e32 v[116:117], 0
	v_mov_b64_e32 v[118:119], 0
	v_mov_b64_e32 v[120:121], 0
	v_mov_b64_e32 v[122:123], 0
	v_mov_b64_e32 v[124:125], 0
	v_mov_b64_e32 v[126:127], 0
	s_addc_u32 s52, s29, 0
	s_mov_b32 s53, -2

; template <class Epi, bool ALIGN_EPI = PG8_ALIGN>
; __device__ __forceinline__ void gemm_phase(LAS unsigned char* lds, const Gemm g, const StaticOrder S, const Epi E) {
;     ...
;         const bool has_next = S.next(ui + 1, nxt);
;         const char* nA = has_next ? (const char*)g.A + (size_t)nxt.pm * tstepA : cA; const char* nB = has_next ? (const char*)g.Bt + (size_t)nxt.pn * tstepB : cB;
;         for (int t = 0; t < nt; t += 2) {
;             const bool last = (t == nt - 2);
;             const char* a1 = cA + (size_t)(t + 1) * kstep;
;             const char* a2 = last ? nA : cA + (size_t)(t + 2) * kstep; const char* b2 = last ? nB : cB + (size_t)(t + 2) * kstep;
;             const char* a3 = a2 + kstep; const char* b3 = b2 + kstep;
;     ...
; #pragma unroll
;         for (int a = 0; a < 2; ++a)
; #pragma unroll
;             for (int b = 0; b < 2; ++b)
; #pragma unroll
;                 for (int m = 0; m < 4; ++m)
; #pragma unroll
;                     for (int n = 0; n < 2; ++n) acc[a][b][m][n] = (f32x4){0.f, 0.f, 0.f, 0.f};
;         cur = nxt; cA = nA; cB = nB; ++ui;
.LBB0_1771:
	s_add_u32 s24, s24, 0x160080
	s_addc_u32 s25, s25, 0
	s_add_u32 s50, s26, 0x100
	v_mov_b64_e32 v[0:1], 0
	v_mov_b64_e32 v[2:3], 0
	v_mov_b64_e32 v[4:5], 0
	v_mov_b64_e32 v[6:7], 0
	v_mov_b64_e32 v[8:9], 0
	v_mov_b64_e32 v[10:11], 0
	v_mov_b64_e32 v[12:13], 0
	v_mov_b64_e32 v[14:15], 0
	v_mov_b64_e32 v[16:17], 0
	v_mov_b64_e32 v[18:19], 0
	v_mov_b64_e32 v[20:21], 0
	v_mov_b64_e32 v[22:23], 0
	v_mov_b64_e32 v[24:25], 0
	v_mov_b64_e32 v[26:27], 0
	v_mov_b64_e32 v[28:29], 0
	v_mov_b64_e32 v[30:31], 0
	v_mov_b64_e32 v[32:33], 0
	v_mov_b64_e32 v[34:35], 0
	v_mov_b64_e32 v[36:37], 0
	v_mov_b64_e32 v[38:39], 0
	v_mov_b64_e32 v[40:41], 0
	v_mov_b64_e32 v[42:43], 0
	v_mov_b64_e32 v[44:45], 0
	v_mov_b64_e32 v[46:47], 0
	v_mov_b64_e32 v[48:49], 0
	v_mov_b64_e32 v[50:51], 0
	v_mov_b64_e32 v[52:53], 0
	v_mov_b64_e32 v[54:55], 0
	v_mov_b64_e32 v[56:57], 0
	v_mov_b64_e32 v[58:59], 0
	v_mov_b64_e32 v[60:61], 0
	v_mov_b64_e32 v[62:63], 0
	v_mov_b64_e32 v[64:65], 0
	v_mov_b64_e32 v[66:67], 0
	v_mov_b64_e32 v[68:69], 0
	v_mov_b64_e32 v[70:71], 0
	v_mov_b64_e32 v[72:73], 0
	v_mov_b64_e32 v[74:75], 0
	v_mov_b64_e32 v[76:77], 0
	v_mov_b64_e32 v[78:79], 0
	v_mov_b64_e32 v[80:81], 0
	v_mov_b64_e32 v[82:83], 0
	v_mov_b64_e32 v[84:85], 0
	v_mov_b64_e32 v[86:87], 0
	v_mov_b64_e32 v[88:89], 0
	v_mov_b64_e32 v[90:91], 0
	v_mov_b64_e32 v[92:93], 0
	v_mov_b64_e32 v[94:95], 0
	v_mov_b64_e32 v[96:97], 0
	v_mov_b64_e32 v[98:99], 0
	v_mov_b64_e32 v[100:101], 0
	v_mov_b64_e32 v[102:103], 0
	v_mov_b64_e32 v[104:105], 0
	v_mov_b64_e32 v[106:107], 0
	v_mov_b64_e32 v[108:109], 0
	v_mov_b64_e32 v[110:111], 0
	v_mov_b64_e32 v[112:113], 0
	v_mov_b64_e32 v[114:115], 0
	v_mov_b64_e32 v[116:117], 0
	v_mov_b64_e32 v[118:119], 0
	v_mov_b64_e32 v[120:121], 0
	v_mov_b64_e32 v[122:123], 0
	v_mov_b64_e32 v[124:125], 0
	v_mov_b64_e32 v[126:127], 0
	s_addc_u32 s51, s27, 0
	s_mov_b32 s52, -2
